# team barrier fast path: arrive with a returning L2 atomic and poll the counter with add-0 atomics instead of sc1 loads
# speedup vs baseline: 1.0009x; 1.0009x over previous
; __device__ __forceinline__ unsigned xb_ld(unsigned* p)              { return __hip_atomic_load(p, __ATOMIC_RELAXED, __HIP_MEMORY_SCOPE_AGENT); }
; __device__ __forceinline__ unsigned xb_add(unsigned* p, unsigned v) { return __hip_atomic_fetch_add(p, v, __ATOMIC_RELAXED, __HIP_MEMORY_SCOPE_AGENT); }
; #define XB_SPIN(cond, bar) do { unsigned _sp = 0; while (cond) { __builtin_amdgcn_s_sleep(1); \
;     if ((++_sp & 255u) == 0u) { if (xb_ld(&(bar)[XB_TMO])) break; if (_sp > XB_SPIN_CAP) { atomicAdd(&(bar)[XB_TMO], 1u); break; } } } } while (0)
; __device__ __forceinline__ void xcd_barrier(const XcdBarrier& b) {
;     ...
;         const unsigned old = xb_add(&bar[XB_XSUB(b.x)], 1u);
;         const unsigned gen = old / nloc;
;         if (old + 1u == (gen + 1u) * nloc) {
;             __builtin_amdgcn_fence(__ATOMIC_RELEASE, "agent");
;             asm volatile("s_waitcnt vmcnt(0)" ::: "memory");
;             const unsigned og = xb_add(&bar[XB_TOP], 1u);
;             const unsigned tg = og / nx;
;             if (og + 1u == (tg + 1u) * nx) xb_add(&bar[XB_TOPGEN], 1u);
;             else XB_SPIN(xb_ld(&bar[XB_TOPGEN]) == tg, bar);
;             __builtin_amdgcn_fence(__ATOMIC_ACQUIRE, "agent");
;             xb_add(&bar[XB_XGEN(b.x)], 1u);
;             asm volatile("s_waitcnt vmcnt(0)" ::: "memory");
;         } else {
;             XB_SPIN(xb_ld(&bar[XB_XGEN(b.x)]) == gen, bar);
;             __builtin_amdgcn_fence(__ATOMIC_ACQUIRE, "agent");
;             asm volatile("s_waitcnt vmcnt(0)" ::: "memory");
.Ltb307_fast:
	global_atomic_add v3, v0, v1, s[8:9] sc0
	buffer_inv sc1
	v_mov_b32_e32 v6, 0
	s_waitcnt vmcnt(0)
	v_add_u32_e32 v3, 1, v3
	v_cmp_ge_u32_e32 vcc, v3, v2
	s_cbranch_vccnz .Ltb307_frel
.Ltb307_spin:
	global_atomic_add v3, v0, v6, s[8:9] sc0
	s_waitcnt vmcnt(0)
	v_cmp_ge_u32_e32 vcc, v3, v2
	s_cbranch_vccnz .Ltb307_frel
	s_sleep 1
	s_add_u32 s15, s15, 1
	s_cmp_lt_u32 s15, 0x400000
	s_cbranch_scc1 .Ltb307_spin
